# attention: Q fragments resident in VGPRs (4 fewer ds_read_b128 per QK block); tile-loop LDS-DMA issued in SGPR-base form without 64-bit address VALU or m0 save/restore
# speedup vs baseline: 1.0126x; 1.0126x over previous
.LBB0_1170:
	v_and_b32_e32 v3, 63, v0
	v_lshrrev_b32_e32 v46, 5, v3
	v_lshlrev_b32_e32 v3, 2, v0
	v_bfe_u32 v4, v0, 2, 2
	v_and_b32_e32 v9, 31, v0
	v_and_or_b32 v3, v3, 12, v4
	v_or_b32_e32 v4, s19, v46
	v_lshl_add_u32 v5, v9, 8, 0
	v_bitop3_b32 v6, v46, v3, s19 bitop3:0x36
	v_lshl_add_u32 v154, v6, 4, v5
	v_bitop3_b32 v6, v4, v3, 2 bitop3:0x36
	v_lshl_add_u32 v155, v6, 4, v5
	v_bitop3_b32 v6, v4, v3, 4 bitop3:0x36
	v_bitop3_b32 v3, v4, v3, 6 bitop3:0x36
	v_lshlrev_b32_e32 v1, 1, v1
	v_lshl_add_u32 v157, v3, 4, v5
	v_and_b32_e32 v1, 2, v1
	v_bfe_u32 v3, v0, 1, 1
	v_lshl_add_u32 v156, v6, 4, v5
	v_bitop3_b32 v5, v1, v46, v3 bitop3:0x36
	v_lshrrev_b32_e32 v2, 2, v2
	v_lshlrev_b32_e32 v47, 4, v5
	v_or_b32_e32 v5, 2, v46
	v_lshlrev_b32_e32 v4, 8, v2
	v_bitop3_b32 v1, v1, v5, v3 bitop3:0x36
	v_lshlrev_b32_e32 v0, 3, v0
	v_lshl_or_b32 v4, v46, 10, v4
	v_lshlrev_b32_e32 v1, 4, v1
	s_movk_i32 s61, 0x800
	v_readlane_b32 s40, v253, 4
	v_and_or_b32 v0, v0, 8, 0
	v_lshlrev_b32_e32 v2, 6, v2
	v_or3_b32 v159, v4, v1, s61
	s_movk_i32 s61, 0x80
	s_add_i32 s40, s40, s3
	v_xad_u32 v162, v2, s61, v0
	s_movk_i32 s61, 0xc0
	s_sub_i32 s38, s15, s3
	s_min_u32 s15, s40, s15
	v_xad_u32 v163, v2, s61, v0
	s_mov_b32 s61, s25
	s_add_i32 s35, s35, s15
	v_add_u32_e32 v158, v0, v2
	v_xad_u32 v160, v2, 64, v0
	s_waitcnt vmcnt(0) lgkmcnt(0)
	s_barrier
	s_lshr_b32 s15, s35, 6
	v_add_u32_e32 v10, s61, v154
	v_add_u32_e32 v22, s61, v155
	v_add_u32_e32 v34, s61, v156
	s_or_b32 s35, s3, s13
	v_add_u32_e32 v68, v4, v158
	v_add_u32_e32 v69, v160, v4
	v_add_u32_e32 v70, v162, v4
	v_add_u32_e32 v71, v163, v4
	ds_read_b128 v[0:3], v154
	ds_read_b128 v[4:7], v154 offset:8192
	ds_read_b128 v[10:13], v10
	ds_read_b128 v[14:17], v155
	ds_read_b128 v[18:21], v155 offset:8192
	ds_read_b128 v[22:25], v22
	ds_read_b128 v[26:29], v156
	ds_read_b128 v[30:33], v156 offset:8192
	ds_read_b128 v[34:37], v34
	ds_read_b128 v[38:41], v157
	ds_read_b128 v[42:45], v157 offset:8192
	v_add_u32_e32 v48, s61, v157
	s_add_i32 vcc_lo, s12, s35
	s_min_i32 s38, s38, 0x80
	ds_read_b128 v[64:67], v48
	s_cmp_lt_i32 s13, s38
	s_cselect_b64 s[40:41], -1, 0
	s_and_b64 s[62:63], s[40:41], exec
	s_mov_b32 s60, 0
	s_cselect_b32 s15, s15, 0
	s_lshr_b32 s17, s17, 6
	s_waitcnt lgkmcnt(9)
	v_mfma_f32_32x32x16_bf16 v[96:111], v[0:3], v[10:13], 0
	s_mov_b32 s61, s60
	s_mov_b32 s62, s60
	s_mov_b32 s63, s60
	s_mov_b32 s64, s60
	s_mov_b32 s65, s60
	s_mov_b32 s66, s60
	s_mov_b32 s67, s60
	v_mfma_f32_32x32x16_bf16 v[80:95], v[4:7], v[10:13], 0
	s_mov_b32 s68, s60
	s_mov_b32 s69, s60
	s_mov_b32 s70, s60
	s_mov_b32 s71, s60
	s_mov_b32 s72, s60
	s_mov_b32 s73, s60
	s_mov_b32 s74, s60
	s_waitcnt lgkmcnt(6)
	v_mfma_f32_32x32x16_bf16 v[96:111], v[14:17], v[22:25], v[96:111]
	s_mov_b32 s75, s60
	v_mov_b64_e32 v[48:49], s[60:61]
	v_mov_b64_e32 v[50:51], s[62:63]
	v_mov_b64_e32 v[52:53], s[64:65]
	v_mov_b64_e32 v[54:55], s[66:67]
	v_mov_b64_e32 v[56:57], s[68:69]
	v_mov_b64_e32 v[58:59], s[70:71]
	v_mfma_f32_32x32x16_bf16 v[80:95], v[18:21], v[22:25], v[80:95]
	v_mov_b64_e32 v[60:61], s[72:73]
	v_mov_b64_e32 v[62:63], s[74:75]
	s_add_i32 s61, s15, -1
	s_add_i32 s72, vcc_lo, 0xffffff66
	s_add_u32 s62, s44, 0x60000
	s_addc_u32 s63, s45, 0
	s_add_i32 s3, s13, s3
	s_waitcnt lgkmcnt(3)
	v_mfma_f32_32x32x16_bf16 v[96:111], v[26:29], v[34:37], v[96:111]
	s_add_i32 s3, s3, s12
	s_waitcnt vmcnt(0) lgkmcnt(0)
	s_barrier
	v_lshlrev_b32_e32 v0, 4, v46
	v_add_lshl_u32 v1, s3, v9, 2
	v_sub_u32_e32 v0, v0, v1
	v_mfma_f32_32x32x16_bf16 v[80:95], v[30:33], v[34:37], v[80:95]
	s_add_u32 s64, s42, 0x40000
	v_add_u32_e32 v166, v47, v68
	v_add_u32_e32 v167, v47, v69
	v_add_u32_e32 v168, v47, v70
	v_add_u32_e32 v169, v47, v71
	v_mov_b64_e32 v[16:17], v[48:49]
	v_add_u32_e32 v164, 0, v0
	s_waitcnt lgkmcnt(0)
	v_mfma_f32_32x32x16_bf16 v[96:111], v[38:41], v[64:67], v[96:111]
	s_addc_u32 s65, s43, 0
	v_mov_b32_e32 v165, 0
	v_mov_b64_e32 v[18:19], v[50:51]
	v_mov_b64_e32 v[20:21], v[52:53]
	v_mov_b64_e32 v[22:23], v[54:55]
	v_mov_b64_e32 v[24:25], v[56:57]
	v_mov_b64_e32 v[26:27], v[58:59]
	v_mfma_f32_32x32x16_bf16 v[80:95], v[42:45], v[64:67], v[80:95]
	v_mov_b64_e32 v[78:79], v[62:63]
	v_mov_b64_e32 v[32:33], v[48:49]
	v_mov_b64_e32 v[76:77], v[60:61]
	v_mov_b64_e32 v[74:75], v[58:59]
	v_mov_b64_e32 v[72:73], v[56:57]
	v_mov_b64_e32 v[70:71], v[54:55]
	v_mov_b64_e32 v[68:69], v[52:53]
	v_mov_b64_e32 v[66:67], v[50:51]
	v_mov_b64_e32 v[64:65], v[48:49]
	v_mov_b64_e32 v[34:35], v[50:51]
	v_mov_b64_e32 v[36:37], v[52:53]
	v_mov_b64_e32 v[38:39], v[54:55]
	v_mov_b64_e32 v[40:41], v[56:57]
	v_mov_b64_e32 v[42:43], v[58:59]
	v_mov_b64_e32 v[44:45], v[60:61]
	v_mov_b64_e32 v[46:47], v[62:63]
	v_mov_b64_e32 v[28:29], v[60:61]
	v_mov_b64_e32 v[30:31], v[62:63]
	v_mov_b32_e32 v161, 0
	v_add_u32_e32 v158, v159, v158
	v_add_u32_e32 v160, v159, v160
	v_add_u32_e32 v162, v159, v162
	v_add_u32_e32 v163, v159, v163
	v_add_u32_e32 v250, s25, v154
	ds_read_b128 v[238:241], v250
	v_add_u32_e32 v250, s25, v155
	ds_read_b128 v[242:245], v250
	v_add_u32_e32 v250, s25, v156
	ds_read_b128 v[246:249], v250
	v_add_u32_e32 v250, s25, v157
	ds_read_b128 v[234:237], v250
	s_waitcnt lgkmcnt(0)
.LBB0_1171:
	s_add_i32 s12, s74, 2
	s_cmp_lt_u32 s12, s17
	s_cselect_b64 s[68:69], -1, 0
	s_cmp_ge_u32 s12, s17
	s_cselect_b64 s[66:67], -1, 0
	s_and_b64 vcc, exec, s[66:67]
	s_cbranch_vccnz .LBB0_1173
	s_add_u32 s42, s62, 0xfffe0000
	s_addc_u32 s43, s63, -1
	s_mov_b32 m0, s21
	s_nop 0
	global_load_lds_dwordx4 v150, s[42:43]
	s_mov_b32 m0, s22
	s_nop 0
	global_load_lds_dwordx4 v144, s[42:43]
.LBB0_1173:
	s_add_i32 s75, s74, 1
	s_cmp_lt_u32 s75, s17
	s_cselect_b64 s[70:71], -1, 0
	s_cmp_ge_u32 s75, s17
	s_cbranch_scc1 .LBB0_1177
	s_add_u32 s42, s64, 0xfffe0000
	s_addc_u32 s43, s65, -1
	s_mov_b32 m0, s26
	s_nop 0
	global_load_lds_dwordx4 v150, s[42:43]
	s_add_i32 s3, s26, 0x400
	s_mov_b32 m0, s3
	s_nop 0
	global_load_lds_dwordx4 v144, s[42:43]
	s_cmp_le_i32 s60, s72
	s_cbranch_scc0 .LBB0_1178

.LBB0_1183:
	s_andn2_b64 s[42:43], exec, s[70:71]
	s_andn2_b64 vcc, exec, s[70:71]
	s_cbranch_vccnz .LBB0_1185
	ds_read_b128 v[0:3], v154 offset:16384
	ds_read_b128 v[4:7], v154 offset:24576
	ds_read_b128 v[170:173], v155 offset:16384
	ds_read_b128 v[174:177], v155 offset:24576
	ds_read_b128 v[182:185], v156 offset:16384
	ds_read_b128 v[186:189], v156 offset:24576
	ds_read_b128 v[194:197], v157 offset:16384
	ds_read_b128 v[226:229], v157 offset:24576
	s_waitcnt lgkmcnt(6)
	v_mfma_f32_32x32x16_bf16 v[128:143], v[0:3], v[238:241], 0
	v_mfma_f32_32x32x16_bf16 v[112:127], v[4:7], v[238:241], 0
	s_waitcnt lgkmcnt(4)
	v_mfma_f32_32x32x16_bf16 v[128:143], v[170:173], v[242:245], v[128:143]
	v_mfma_f32_32x32x16_bf16 v[112:127], v[174:177], v[242:245], v[112:127]
	s_waitcnt lgkmcnt(2)
	v_mfma_f32_32x32x16_bf16 v[128:143], v[182:185], v[246:249], v[128:143]
	v_mfma_f32_32x32x16_bf16 v[112:127], v[186:189], v[246:249], v[112:127]
	s_waitcnt lgkmcnt(0)
	v_mfma_f32_32x32x16_bf16 v[128:143], v[194:197], v[234:237], v[128:143]
	v_mfma_f32_32x32x16_bf16 v[112:127], v[226:229], v[234:237], v[112:127]
.LBB0_1185:
	ds_read_b64_tr_b16 v[0:1], v166 offset:32768
	ds_read_b64_tr_b16 v[2:3], v158 offset:32768
	ds_read_b64_tr_b16 v[4:5], v167 offset:32768
	ds_read_b64_tr_b16 v[6:7], v160 offset:32768
	ds_read_b64_tr_b16 v[10:11], v168 offset:32768
	ds_read_b64_tr_b16 v[12:13], v162 offset:32768
	ds_read_b64_tr_b16 v[174:175], v169 offset:32768
	ds_read_b64_tr_b16 v[176:177], v163 offset:32768
	v_exp_f32_e32 v96, v96
	v_exp_f32_e32 v80, v80
	v_exp_f32_e32 v97, v97
	v_exp_f32_e32 v81, v81
	v_add_f32_e32 v9, 0, v96
	v_exp_f32_e32 v98, v98
	v_add_f32_e32 v9, v80, v9
	v_exp_f32_e32 v82, v82
	v_add_f32_e32 v9, v97, v9
	v_exp_f32_e32 v99, v99
	v_add_f32_e32 v9, v81, v9
	v_exp_f32_e32 v83, v83
	v_add_f32_e32 v9, v98, v9
	v_exp_f32_e32 v100, v100
	v_add_f32_e32 v9, v82, v9
	v_exp_f32_e32 v84, v84
	v_add_f32_e32 v9, v99, v9
	v_exp_f32_e32 v101, v101
	v_add_f32_e32 v9, v83, v9
	v_exp_f32_e32 v85, v85
	v_add_f32_e32 v9, v100, v9
	v_exp_f32_e32 v102, v102
	v_add_f32_e32 v9, v84, v9
	v_exp_f32_e32 v86, v86
	v_add_f32_e32 v9, v101, v9
	v_exp_f32_e32 v103, v103
	v_add_f32_e32 v9, v85, v9
	v_exp_f32_e32 v87, v87
	v_add_f32_e32 v9, v102, v9
	v_exp_f32_e32 v104, v104
	v_add_f32_e32 v9, v86, v9
	v_exp_f32_e32 v88, v88
	v_add_f32_e32 v9, v103, v9
	v_exp_f32_e32 v105, v105
	v_add_f32_e32 v9, v87, v9
	v_exp_f32_e32 v89, v89
	v_add_f32_e32 v9, v104, v9
	v_exp_f32_e32 v106, v106
	v_add_f32_e32 v9, v88, v9
	v_exp_f32_e32 v90, v90
	v_add_f32_e32 v9, v105, v9
	v_exp_f32_e32 v107, v107
	v_add_f32_e32 v9, v89, v9
	v_exp_f32_e32 v91, v91
	v_add_f32_e32 v9, v106, v9
	v_exp_f32_e32 v108, v108
	v_add_f32_e32 v9, v90, v9
	v_exp_f32_e32 v92, v92
	v_add_f32_e32 v9, v107, v9
	v_exp_f32_e32 v109, v109
	v_add_f32_e32 v9, v91, v9
	v_exp_f32_e32 v93, v93
	v_add_f32_e32 v9, v108, v9
	v_exp_f32_e32 v110, v110
	v_add_f32_e32 v9, v92, v9
	v_exp_f32_e32 v94, v94
	v_add_f32_e32 v9, v109, v9
	v_exp_f32_e32 v111, v111
	v_add_f32_e32 v9, v93, v9
	v_exp_f32_e32 v95, v95
	v_add_f32_e32 v9, v110, v9
	v_add_f32_e32 v9, v94, v9
	v_add_f32_e32 v9, v111, v9
	v_add_f32_e32 v9, v95, v9
	ds_read_b64_tr_b16 v[178:179], v166 offset:36864
	ds_read_b64_tr_b16 v[180:181], v158 offset:36864
	ds_read_b64_tr_b16 v[182:183], v167 offset:36864
	ds_read_b64_tr_b16 v[184:185], v160 offset:36864
	ds_read_b64_tr_b16 v[186:187], v168 offset:36864
	ds_read_b64_tr_b16 v[188:189], v162 offset:36864
	ds_read_b64_tr_b16 v[190:191], v169 offset:36864
	ds_read_b64_tr_b16 v[192:193], v163 offset:36864
	v_cvt_pk_bf16_f32 v194, v96, v97
	v_cvt_pk_bf16_f32 v195, v98, v99
	v_cvt_pk_bf16_f32 v196, v100, v101
	v_cvt_pk_bf16_f32 v197, v102, v103
	s_waitcnt lgkmcnt(14)
	s_nop 0
	v_mfma_f32_32x32x16_bf16 v[48:63], v[0:3], v[194:197], v[48:63]
	s_waitcnt lgkmcnt(12)
	v_mfma_f32_32x32x16_bf16 v[64:79], v[4:7], v[194:197], v[64:79]
	s_waitcnt lgkmcnt(10)
	v_mfma_f32_32x32x16_bf16 v[32:47], v[10:13], v[194:197], v[32:47]
	s_waitcnt lgkmcnt(8)
	v_mfma_f32_32x32x16_bf16 v[16:31], v[174:177], v[194:197], v[16:31]
	ds_read_b64_tr_b16 v[0:1], v166 offset:40960
	ds_read_b64_tr_b16 v[2:3], v158 offset:40960
	ds_read_b64_tr_b16 v[4:5], v167 offset:40960
	ds_read_b64_tr_b16 v[6:7], v160 offset:40960
	ds_read_b64_tr_b16 v[10:11], v168 offset:40960
	ds_read_b64_tr_b16 v[12:13], v162 offset:40960
	ds_read_b64_tr_b16 v[174:175], v169 offset:40960
	ds_read_b64_tr_b16 v[176:177], v163 offset:40960
	v_cvt_pk_bf16_f32 v194, v104, v105
	v_cvt_pk_bf16_f32 v195, v106, v107
	v_cvt_pk_bf16_f32 v196, v108, v109
	v_cvt_pk_bf16_f32 v197, v110, v111
	s_waitcnt lgkmcnt(14)
	s_nop 0
	v_mfma_f32_32x32x16_bf16 v[48:63], v[178:181], v[194:197], v[48:63]
	s_waitcnt lgkmcnt(12)
	v_mfma_f32_32x32x16_bf16 v[64:79], v[182:185], v[194:197], v[64:79]
	s_waitcnt lgkmcnt(10)
	v_mfma_f32_32x32x16_bf16 v[32:47], v[186:189], v[194:197], v[32:47]
	s_waitcnt lgkmcnt(8)
	v_mfma_f32_32x32x16_bf16 v[16:31], v[190:193], v[194:197], v[16:31]
	ds_read_b64_tr_b16 v[178:179], v166 offset:45056
	ds_read_b64_tr_b16 v[180:181], v158 offset:45056
	ds_read_b64_tr_b16 v[182:183], v167 offset:45056
	ds_read_b64_tr_b16 v[184:185], v160 offset:45056
	ds_read_b64_tr_b16 v[186:187], v168 offset:45056
	ds_read_b64_tr_b16 v[188:189], v162 offset:45056
	ds_read_b64_tr_b16 v[190:191], v169 offset:45056
	ds_read_b64_tr_b16 v[192:193], v163 offset:45056
	v_cvt_pk_bf16_f32 v194, v80, v81
	v_cvt_pk_bf16_f32 v195, v82, v83
	v_cvt_pk_bf16_f32 v196, v84, v85
	v_cvt_pk_bf16_f32 v197, v86, v87
	s_waitcnt lgkmcnt(14)
	s_nop 0
	v_mfma_f32_32x32x16_bf16 v[48:63], v[0:3], v[194:197], v[48:63]
	s_waitcnt lgkmcnt(12)
	v_mfma_f32_32x32x16_bf16 v[64:79], v[4:7], v[194:197], v[64:79]
	s_waitcnt lgkmcnt(10)
	v_mfma_f32_32x32x16_bf16 v[32:47], v[10:13], v[194:197], v[32:47]
	s_waitcnt lgkmcnt(8)
	v_mfma_f32_32x32x16_bf16 v[16:31], v[174:177], v[194:197], v[16:31]
	v_cvt_pk_bf16_f32 v0, v88, v89
	v_cvt_pk_bf16_f32 v1, v90, v91
	v_cvt_pk_bf16_f32 v2, v92, v93
	v_cvt_pk_bf16_f32 v3, v94, v95
	s_waitcnt vmcnt(0) lgkmcnt(0)
	s_barrier
	v_add_f32_e32 v161, v161, v9
	s_waitcnt lgkmcnt(6)
	v_mfma_f32_32x32x16_bf16 v[48:63], v[178:181], v[0:3], v[48:63]
	s_and_b64 vcc, exec, s[42:43]
	s_waitcnt lgkmcnt(4)
	v_mfma_f32_32x32x16_bf16 v[64:79], v[182:185], v[0:3], v[64:79]
	s_waitcnt lgkmcnt(2)
	v_mfma_f32_32x32x16_bf16 v[32:47], v[186:189], v[0:3], v[32:47]
	s_waitcnt lgkmcnt(0)
	v_mfma_f32_32x32x16_bf16 v[16:31], v[190:193], v[0:3], v[16:31]
	s_cbranch_vccnz .LBB0_1197
	s_add_i32 s3, s74, 3
	s_cmp_ge_u32 s3, s17
	s_cbranch_scc1 .LBB0_1199
	s_mov_b32 m0, s27
	s_nop 0
	global_load_lds_dwordx4 v150, s[62:63]
	s_add_i32 s3, s27, 0x400
	s_mov_b32 m0, s3
	s_nop 0
	global_load_lds_dwordx4 v144, s[62:63]
	s_andn2_b64 s[42:43], exec, s[68:69]
	s_andn2_b64 vcc, exec, s[68:69]
	s_cbranch_vccz .LBB0_1200

.LBB0_1194:
	s_and_b64 vcc, exec, s[42:43]
	s_cbranch_vccnz .LBB0_1196
	ds_read_b128 v[0:3], v154
	ds_read_b128 v[4:7], v154 offset:8192
	ds_read_b128 v[174:177], v155
	ds_read_b128 v[178:181], v155 offset:8192
	ds_read_b128 v[186:189], v156
	ds_read_b128 v[190:193], v156 offset:8192
	ds_read_b128 v[226:229], v157
	ds_read_b128 v[230:233], v157 offset:8192
	s_waitcnt lgkmcnt(6)
	v_mfma_f32_32x32x16_bf16 v[96:111], v[0:3], v[238:241], 0
	v_mfma_f32_32x32x16_bf16 v[80:95], v[4:7], v[238:241], 0
	s_waitcnt lgkmcnt(4)
	v_mfma_f32_32x32x16_bf16 v[96:111], v[174:177], v[242:245], v[96:111]
	v_mfma_f32_32x32x16_bf16 v[80:95], v[178:181], v[242:245], v[80:95]
	s_waitcnt lgkmcnt(2)
	v_mfma_f32_32x32x16_bf16 v[96:111], v[186:189], v[246:249], v[96:111]
	v_mfma_f32_32x32x16_bf16 v[80:95], v[190:193], v[246:249], v[80:95]
	s_waitcnt lgkmcnt(0)
	v_mfma_f32_32x32x16_bf16 v[96:111], v[226:229], v[234:237], v[96:111]
	v_mfma_f32_32x32x16_bf16 v[80:95], v[230:233], v[234:237], v[80:95]

.LBB0_1200:
	s_mov_b32 m0, s23
	s_nop 0
	global_load_lds_dwordx4 v150, s[64:65]
	s_mov_b32 m0, s24
	s_nop 0
	global_load_lds_dwordx4 v144, s[64:65]
	s_add_i32 s3, s60, 64
	s_cmp_le_i32 s3, s72
	s_cbranch_scc0 .LBB0_1189
